# on top of previous: HGRN2 staging no longer computes or stores the unused F operand; end-of-block barrier kept only on the exit path (combine reads PO, next staging writes K/Q/V: disjoint)
# speedup vs baseline: 1.0082x; 1.0082x over previous
; DI float bf2f(bf16_t b) { return __uint_as_float(((unsigned)b) << 16); }
; DI float sigmoidf_(float x) { return __builtin_amdgcn_rcpf(1.0f + __builtin_amdgcn_exp2f(-1.4426950408889634f * x)); }
; DI float siluf_(float x) { return x * __builtin_amdgcn_rcpf(1.0f + __builtin_amdgcn_exp2f(-1.4426950408889634f * x)); }
; #define HG_PREFETCH(T0) do { _Pragma("unroll") for (int i = 0; i < 4; ++i) { const bf16_t* row = base + (size_t)((T0) + wv * 4 + i) * PLD; \
;         pz[i] = row[C_HF]; pq[i] = row[C_HQ]; pi[i] = row[C_HI]; pg[i] = row[C_HG]; } } while (0)
; __device__ __forceinline__ void hgrn_scan(unsigned char* smem, CP p, int L, int b, int h) {
;     ...
;     HG_PREFETCH(0);
;     for (int t0 = 0; t0 < SEQ; t0 += 32) {
;         float gr[4];
; #pragma unroll
;         for (int i = 0; i < 4; ++i) { const int t = wv * 4 + i;
;             const float z = bf2f(pz[i]), qr = bf2f(pq[i]), vi = bf2f(pi[i]); gr[i] = bf2f(pg[i]);
;             const float sg = sigmoidf_(z); F[t * 64 + e] = sg + lb * (1.0f - sg); Kx[t * 64 + e] = (1.0f - lb) * (1.0f - sg); Q[t * 64 + e] = siluf_(qr); V[t * 64 + e] = vi; }
;         __syncthreads();
;         if (t0 + 32 < SEQ) HG_PREFETCH(t0 + 32);
.LBB0_650:
	v_lshlrev_b32_e32 v35, 16, v24
	v_mul_f32_e32 v38, 0xbfb8aa3b, v35
	v_exp_f32_e32 v38, v38
	v_lshlrev_b32_e32 v0, 16, v25
	v_mul_f32_e32 v0, 0xbfb8aa3b, v0
	v_exp_f32_e32 v0, v0
	v_add_f32_e32 v38, 1.0, v38
	v_rcp_f32_e32 v38, v38
	v_and_b32_e32 v39, 0xffff0000, v24
	v_add_f32_e32 v0, 1.0, v0
	v_rcp_f32_e32 v0, v0
	v_mul_f32_e32 v35, v38, v35
	v_and_b32_e32 v38, 0xffff0000, v25
	v_mul_f32_e32 v38, 0xbfb8aa3b, v38
	v_exp_f32_e32 v38, v38
	v_sub_f32_e32 v37, 1.0, v0
	v_mul_f32_e32 v37, v20, v37
	v_add_f32_e32 v38, 1.0, v38
	v_rcp_f32_e32 v38, v38
	v_lshlrev_b32_e32 v36, 16, v33
	v_and_b32_e32 v40, 0xffff0000, v33
	s_add_i32 s7, s6, 32
	v_sub_f32_e32 v41, 1.0, v38
	v_mul_f32_e32 v0, v20, v41
	ds_write2st64_b32 v23, v37, v0 offset0:32 offset1:33
	v_mul_f32_e32 v0, 0xbfb8aa3b, v39
	v_exp_f32_e32 v0, v0
	s_cmpk_gt_u32 s6, 0x7df
	s_cselect_b64 s[4:5], -1, 0
	s_and_b64 vcc, exec, s[4:5]
	v_add_f32_e32 v0, 1.0, v0
	v_rcp_f32_e32 v0, v0
	s_nop 0
	v_mul_f32_e32 v0, v0, v39
	ds_write2st64_b32 v23, v35, v0 offset0:64 offset1:65
	ds_write2st64_b32 v23, v36, v40 offset0:96 offset1:97
	v_lshlrev_b32_e32 v35, 16, v26
	v_mul_f32_e32 v38, 0xbfb8aa3b, v35
	v_exp_f32_e32 v38, v38
	v_lshlrev_b32_e32 v0, 16, v27
	v_mul_f32_e32 v0, 0xbfb8aa3b, v0
	v_exp_f32_e32 v0, v0
	v_add_f32_e32 v38, 1.0, v38
	v_rcp_f32_e32 v38, v38
	v_and_b32_e32 v39, 0xffff0000, v26
	v_add_f32_e32 v0, 1.0, v0
	v_rcp_f32_e32 v0, v0
	v_mul_f32_e32 v35, v38, v35
	v_and_b32_e32 v38, 0xffff0000, v27
	v_mul_f32_e32 v38, 0xbfb8aa3b, v38
	v_exp_f32_e32 v38, v38
	v_sub_f32_e32 v37, 1.0, v0
	v_mul_f32_e32 v37, v20, v37
	v_add_f32_e32 v38, 1.0, v38
	v_rcp_f32_e32 v38, v38
	v_lshlrev_b32_e32 v36, 16, v34
	v_and_b32_e32 v40, 0xffff0000, v34
	v_sub_f32_e32 v41, 1.0, v38
	v_mul_f32_e32 v0, v20, v41
	ds_write2st64_b32 v23, v37, v0 offset0:34 offset1:35
	v_mul_f32_e32 v0, 0xbfb8aa3b, v39
	v_exp_f32_e32 v0, v0
	s_nop 0
	v_add_f32_e32 v0, 1.0, v0
	v_rcp_f32_e32 v0, v0
	s_nop 0
	v_mul_f32_e32 v0, v0, v39
	ds_write2st64_b32 v23, v35, v0 offset0:66 offset1:67
	ds_write2st64_b32 v23, v36, v40 offset0:98 offset1:99
	s_waitcnt lgkmcnt(0)
	s_barrier
	s_cbranch_vccnz .LBB0_652
	v_add_u32_e32 v0, s7, v15
	v_mad_i64_i32 v[24:25], s[0:1], v0, s65, v[2:3]
	global_load_ushort v27, v[24:25], off offset:1024
	global_load_ushort v26, v[24:25], off
	global_load_ushort v33, v[24:25], off offset:2048
	global_load_ushort v34, v[24:25], off offset:3072
	v_or_b32_e32 v24, 1, v0
	v_mad_i64_i32 v[24:25], s[0:1], v24, s65, v[2:3]
	global_load_ushort v72, v[24:25], off offset:1024
	global_load_ushort v73, v[24:25], off
	global_load_ushort v74, v[24:25], off offset:2048
	global_load_ushort v35, v[24:25], off offset:3072
	v_or_b32_e32 v24, 2, v0
	v_mad_i64_i32 v[24:25], s[0:1], v24, s65, v[2:3]
	v_or_b32_e32 v0, 3, v0
	global_load_ushort v75, v[24:25], off offset:1024
	global_load_ushort v76, v[24:25], off
	global_load_ushort v77, v[24:25], off offset:2048
	global_load_ushort v78, v[24:25], off offset:3072
	v_mad_i64_i32 v[24:25], s[0:1], v0, s65, v[2:3]
	global_load_ushort v79, v[24:25], off offset:1024
	global_load_ushort v80, v[24:25], off
	global_load_ushort v81, v[24:25], off offset:2048
	s_nop 0
	global_load_ushort v24, v[24:25], off offset:3072
	s_branch .LBB0_653

; DI bf16_t f2bf(float f) { return (bf16_t)(pack2(f, 0.f) & 0xFFFFu); }
; DI float siluf_(float x) { return x * __builtin_amdgcn_rcpf(1.0f + __builtin_amdgcn_exp2f(-1.4426950408889634f * x)); }
; __device__ __forceinline__ void hgrn_scan(unsigned char* smem, CP p, int L, int b, int h) {
;     ...
;             base[(size_t)(t0 + t) * PLD + C_HQ] = f2bf(o * rs * ng * siluf_(gr[i])); }
;         __syncthreads();
;     }
.Lhg_pack_done:
	v_mov_b32_e32 v12, v0
	v_mov_b32_e32 v13, v35
	s_cbranch_vccz .LBB0_650
	s_barrier
	s_mov_b64 s[0:1], 0
